# P1: nt only on the x loads, XN/XN8 stores allocate normally (stay in the memory-side cache for P2); rest of the stack unchanged (static gMLP chunk, top-counter barrier, P2 tail split, nt on gate store
# speedup vs baseline: 1.0229x; 1.0117x over previous
.LBB0_667:
	s_abs_i32 s0, s96
	v_cvt_f32_u32_e32 v1, s0
	s_sub_i32 s1, 0, s0
	v_readlane_b32 s92, v253, 62
	v_readlane_b32 s80, v253, 54
	v_rcp_iflag_f32_e32 v1, v1
	v_readlane_b32 s93, v253, 63
	v_readlane_b32 s81, v253, 55
	v_readlane_b32 s82, v253, 56
	v_mul_f32_e32 v1, 0x4f7ffffe, v1
	v_cvt_u32_f32_e32 v1, v1
	v_readlane_b32 s83, v253, 57
	v_readlane_b32 s84, v253, 58
	v_readlane_b32 s85, v253, 59
	v_readfirstlane_b32 s2, v1
	s_mul_i32 s1, s1, s2
	s_mul_hi_u32 s1, s2, s1
	s_add_i32 s2, s2, s1
	s_mul_hi_u32 s1, s2, 0x784
	s_mul_i32 s1, s1, s0
	s_sub_i32 s1, 0x784, s1
	s_sub_i32 s2, s1, s0
	s_cmp_ge_u32 s1, s0
	s_cselect_b32 s1, s2, s1
	s_sub_i32 s2, s1, s0
	s_cmp_ge_u32 s1, s0
	s_cselect_b32 s0, s2, s1
	s_cmp_lg_u32 s0, 0
	s_cselect_b64 s[2:3], -1, 0
	s_cmp_lt_i32 s97, s0
	s_cselect_b64 s[4:5], -1, 0
	s_and_b64 s[2:3], s[2:3], s[4:5]
	s_and_b64 vcc, exec, s[2:3]
	v_readlane_b32 s86, v253, 60
	v_readlane_b32 s87, v253, 61
	s_cbranch_vccz .Lss_spare
	v_lshrrev_b32_e32 v74, 3, v218
	v_and_b32_e32 v75, 31, v0
	s_movk_i32 s16, 0x84
	s_add_i32 s2, s97, 0x1fc
	s_movk_i32 vcc_lo, 0x1400
	s_nop 0
	v_writelane_b32 v250, vcc_lo, 0
	s_branch .LBB0_677
